# P7 sample-row small GEMM K-loop: software-pipelined two K-steps deep (second staging register set), unrolled by two
# speedup vs baseline: 1.0049x; 1.0049x over previous
;     ...
;         for (int i = 0; i < 16; ++i) { acc0[i] = 0.f; acc1[i] = 0.f; }
;         float q8[8];
; #pragma unroll
;         for (int i = 0; i < 8; ++i) q8[i] = 0.f;
;         int rb = 0, cg = 0;
;         if (act) {
;             rb = task / ncg; cg = task - rb * ncg;
;             const int Kw = K / KS, nb = Kw / 64, k0 = ks * Kw;
;             const bf16_t* b0p = Bt + (size_t)(E.brow(cg, 0) + (lane >> 3)) * K + k0 + 8 * (lane & 7);
;             const bf16_t* b1p = Bt + (size_t)(E.brow(cg, 1) + (lane >> 3)) * K + k0 + 8 * (lane & 7);
;             const float* afp = (const float*)Abase + (size_t)(32 * rb + (lane >> 4)) * K + k0 + 4 * (lane & 15);
;             const bf16_t* abp = (const bf16_t*)Abase + (size_t)(32 * rb + (lane >> 3)) * K + k0 + 8 * (lane & 7);
;             f32x4 xa[8]; u32x4 ab[4], bb0[4], bb1[4];
;     ...
;             SG_LOAD(0);
.LBB0_1345:
	s_mul_i32 s6, s15, s80
	s_add_i32 s6, s14, s6
	s_cmpk_lt_i32 s6, 0x100
	s_cselect_b64 s[10:11], -1, 0
	s_cmpk_gt_i32 s6, 0xff
	s_cbranch_scc1 .LBB0_1349
	s_ashr_i32 s7, s6, 31
	s_lshr_b32 s7, s7, 28
	s_add_i32 s7, s6, s7
	s_ashr_i32 s7, s7, 4
	s_lshl_b32 s12, s7, 10
	s_lshl_b32 s6, s6, 6
	s_sub_i32 s6, s6, s12
	v_or_b32_e32 v2, s6, v83
	v_or_b32_e32 v4, 32, v2
	v_ashrrev_i32_e32 v5, 31, v4
	v_lshlrev_b64 v[4:5], 13, v[4:5]
	v_ashrrev_i32_e32 v3, 31, v2
	v_lshl_add_u64 v[4:5], v[84:85], 0, v[4:5]
	s_mov_b32 s17, 0x30000
	v_lshlrev_b64 v[2:3], 13, v[2:3]
	v_add_co_u32_e32 v10, vcc, s17, v4
	v_lshl_add_u64 v[2:3], v[84:85], 0, v[2:3]
	s_nop 0
	v_addc_co_u32_e32 v11, vcc, 0, v5, vcc
	v_add_co_u32_e32 v12, vcc, s17, v2
	s_mov_b32 s13, 0x20000
	s_nop 0
	v_addc_co_u32_e32 v13, vcc, 0, v3, vcc
	v_add_co_u32_e32 v14, vcc, s13, v4
	s_lshl_b32 s16, s7, 5
	s_nop 0
	v_addc_co_u32_e32 v15, vcc, 0, v5, vcc
	global_load_dwordx4 v[38:41], v[12:13], off
	global_load_dwordx4 v[34:37], v[14:15], off
	v_add_co_u32_e32 v12, vcc, s13, v2
	s_mov_b32 s7, 0x10000
	s_nop 0
	v_addc_co_u32_e32 v13, vcc, 0, v3, vcc
	v_or_b32_e32 v6, s16, v83
	v_add_co_u32_e32 v14, vcc, s7, v4
	v_ashrrev_i32_e32 v7, 31, v6
	s_nop 0
	v_addc_co_u32_e32 v15, vcc, 0, v5, vcc
	v_lshlrev_b64 v[6:7], 13, v[6:7]
	global_load_dwordx4 v[58:61], v[12:13], off
	global_load_dwordx4 v[46:49], v[14:15], off
	v_add_co_u32_e32 v12, vcc, s7, v2
	v_lshl_add_u64 v[8:9], v[86:87], 0, v[6:7]
	s_nop 0
	v_addc_co_u32_e32 v13, vcc, 0, v3, vcc
	global_load_dwordx4 v[74:77], v[10:11], off
	global_load_dwordx4 v[50:53], v[4:5], off
	v_add_co_u32_e32 v4, vcc, s17, v8
	v_lshl_add_u64 v[92:93], v[88:89], 0, v[6:7]
	s_nop 0
	v_addc_co_u32_e32 v5, vcc, 0, v9, vcc
	global_load_dwordx4 v[70:73], v[12:13], off
	global_load_dwordx4 v[42:45], v[4:5], off
	v_add_co_u32_e32 v4, vcc, s13, v8
	s_nop 1
	v_addc_co_u32_e32 v5, vcc, 0, v9, vcc
	v_add_co_u32_e32 v10, vcc, s7, v8
	s_nop 1
	v_addc_co_u32_e32 v11, vcc, 0, v9, vcc
	global_load_dwordx4 v[66:69], v[4:5], off
	global_load_dwordx4 v[54:57], v[10:11], off
	global_load_dwordx4 v[78:81], v[2:3], off
	global_load_dwordx4 v[62:65], v[8:9], off
	v_subrev_u32_e32 v2, s12, v0
	v_ashrrev_i32_e32 v3, 31, v2
	v_lshlrev_b64 v[2:3], 13, v[2:3]
	v_lshl_add_u64 v[94:95], v[90:91], 0, v[2:3]
	v_subrev_u32_e32 v2, s12, v100
	v_ashrrev_i32_e32 v3, 31, v2
	v_lshlrev_b64 v[2:3], 13, v[2:3]
	v_lshl_add_u64 v[96:97], v[90:91], 0, v[2:3]
	v_mov_b32_e32 v2, 0
	s_mov_b64 s[12:13], 0
	v_mov_b32_e32 v3, v2
	v_mov_b32_e32 v4, v2
	v_mov_b32_e32 v5, v2
	v_mov_b32_e32 v6, v2
	v_mov_b32_e32 v7, v2
	v_mov_b32_e32 v8, v2
	v_mov_b32_e32 v9, v2
	v_mov_b32_e32 v10, v2
	v_mov_b32_e32 v11, v2
	v_mov_b32_e32 v12, v2
	v_mov_b32_e32 v13, v2
	v_mov_b32_e32 v14, v2
	v_mov_b32_e32 v15, v2
	v_mov_b32_e32 v16, v2
	v_mov_b32_e32 v17, v2
	v_mov_b32_e32 v18, v2
	v_mov_b32_e32 v19, v2
	v_mov_b32_e32 v20, v2
	v_mov_b32_e32 v21, v2
	v_mov_b32_e32 v22, v2
	v_mov_b32_e32 v23, v2
	v_mov_b32_e32 v24, v2
	v_mov_b32_e32 v25, v2
	v_mov_b32_e32 v26, v2
	v_mov_b32_e32 v27, v2
	v_mov_b32_e32 v28, v2
	v_mov_b32_e32 v29, v2
	v_mov_b32_e32 v30, v2
	v_mov_b32_e32 v31, v2
	v_mov_b32_e32 v32, v2
	v_mov_b32_e32 v33, v2
	v_lshl_add_u64 v[112:113], v[92:93], 0, s[12:13]
	s_mov_b32 s7, 0xfa00000
	v_add_co_u32_e32 v114, vcc, s7, v112
	s_mov_b32 s7, 0xfa10000
	s_nop 0
	v_addc_co_u32_e32 v115, vcc, 0, v113, vcc
	v_add_co_u32_e32 v116, vcc, s7, v112
	s_mov_b32 s7, 0xfa20000
	s_nop 0
	v_addc_co_u32_e32 v117, vcc, 0, v113, vcc
	global_load_dwordx4 v[140:143], v[114:115], off offset:128
	global_load_dwordx4 v[132:135], v[116:117], off offset:128
	v_add_co_u32_e32 v114, vcc, s7, v112
	s_mov_b32 s7, 0xfa30000
	s_nop 0
	v_addc_co_u32_e32 v115, vcc, 0, v113, vcc
	v_add_co_u32_e32 v112, vcc, s7, v112
	v_lshl_add_u64 v[116:117], v[94:95], 0, s[12:13]
	s_nop 0
	v_addc_co_u32_e32 v113, vcc, 0, v113, vcc
	global_load_dwordx4 v[144:147], v[114:115], off offset:128
	global_load_dwordx4 v[120:123], v[112:113], off offset:128
	v_add_co_u32_e32 v112, vcc, s87, v116
	v_lshl_add_u64 v[118:119], v[96:97], 0, s[12:13]
	s_nop 0
	v_addc_co_u32_e32 v113, vcc, 0, v117, vcc
	v_add_co_u32_e32 v114, vcc, s87, v118
	s_nop 1
	v_addc_co_u32_e32 v115, vcc, 0, v119, vcc
	global_load_dwordx4 v[156:159], v[112:113], off offset:128
	global_load_dwordx4 v[128:131], v[114:115], off offset:128
	v_add_co_u32_e32 v112, vcc, s94, v116
	s_nop 1
	v_addc_co_u32_e32 v113, vcc, 0, v117, vcc
	v_add_co_u32_e32 v114, vcc, s94, v118
	s_nop 1
	v_addc_co_u32_e32 v115, vcc, 0, v119, vcc
	global_load_dwordx4 v[148:151], v[112:113], off offset:128
	global_load_dwordx4 v[124:127], v[114:115], off offset:128
	v_add_co_u32_e32 v112, vcc, s95, v116
	s_nop 1
	v_addc_co_u32_e32 v113, vcc, 0, v117, vcc
	v_add_co_u32_e32 v114, vcc, s95, v118
	s_nop 1
	v_addc_co_u32_e32 v115, vcc, 0, v119, vcc
	v_add_co_u32_e32 v116, vcc, s92, v116
	global_load_dwordx4 v[136:139], v[112:113], off offset:128
	s_nop 0
	global_load_dwordx4 v[112:115], v[114:115], off offset:128
	v_addc_co_u32_e32 v117, vcc, 0, v117, vcc
	v_add_co_u32_e32 v152, vcc, s92, v118
	s_nop 1
	v_addc_co_u32_e32 v153, vcc, 0, v119, vcc
	global_load_dwordx4 v[116:119], v[116:117], off offset:128
	s_nop 0
	global_load_dwordx4 v[152:155], v[152:153], off offset:128
; #define LAS __attribute__((address_space(3)))
; __device__ __forceinline__ unsigned cvtpk(float lo, float hi) { f32x2 v = {lo, hi}; bf16x2_t b = __builtin_convertvector(v, bf16x2_t); return __builtin_bit_cast(unsigned, b); }
; #define MFMA32(a, b, c) __builtin_amdgcn_mfma_f32_32x32x16_bf16((a), (b), (c), 0, 0, 0)
;     ...
;             for (int kb = 0; kb < nb; ++kb) {
;                 __builtin_amdgcn_sched_barrier(0);
;                 if constexpr (AF32) {
; #pragma unroll
;                     for (int i = 0; i < 8; ++i) { const f32x4 x = xa[i]; q8[i] += (x[0] * x[0] + x[1] * x[1]) + (x[2] * x[2] + x[3] * x[3]);
;                         u32x2 w; w.x = cvtpk(x[0], x[1]); w.y = cvtpk(x[2], x[3]); *(LAS u32x2*)(SA + (4 * i + (lane >> 4)) * PITCH + 8 * (lane & 15)) = w; }
;                 } else {
; #pragma unroll
;                     for (int i = 0; i < 4; ++i) *(LAS u32x4*)(SA + (8 * i + (lane >> 3)) * PITCH + 16 * (lane & 7)) = ab[i];
;                 }
; #pragma unroll
;                 for (int i = 0; i < 4; ++i) { *(LAS u32x4*)(SB0 + (8 * i + (lane >> 3)) * PITCH + 16 * (lane & 7)) = bb0[i]; *(LAS u32x4*)(SB1 + (8 * i + (lane >> 3)) * PITCH + 16 * (lane & 7)) = bb1[i]; }
;                 __builtin_amdgcn_sched_barrier(0);
;                 if (kb + 1 < nb) SG_LOAD(kb + 1);
;                 __builtin_amdgcn_sched_barrier(0);
; #pragma unroll
;                 for (int j = 0; j < 4; ++j) {
;                     const bf16x8 af = *(const LAS bf16x8*)(SA + r32 * PITCH + 32 * j + 16 * hi);
;                     const bf16x8 f0 = *(const LAS bf16x8*)(SB0 + r32 * PITCH + 32 * j + 16 * hi), f1 = *(const LAS bf16x8*)(SB1 + r32 * PITCH + 32 * j + 16 * hi);
;                     acc0 = MFMA32(af, f0, acc0); acc1 = MFMA32(af, f1, acc1);
;                 }
.LBB0_1347:
	s_waitcnt vmcnt(12)
	ds_write_b128 v101, v[62:65]
	ds_write_b128 v101, v[54:57] offset:1152
	ds_write_b128 v101, v[66:69] offset:2304
	ds_write_b128 v101, v[42:45] offset:3456
	ds_write_b128 v101, v[78:81] offset:4608
	ds_write_b128 v101, v[50:53] offset:9216
	ds_write_b128 v101, v[70:73] offset:5760
	ds_write_b128 v101, v[46:49] offset:10368
	ds_write_b128 v101, v[58:61] offset:6912
	ds_write_b128 v101, v[34:37] offset:11520
	ds_write_b128 v101, v[38:41] offset:8064
	ds_write_b128 v101, v[74:77] offset:12672
	v_lshl_add_u64 v[34:35], v[92:93], 0, s[12:13]
	s_mov_b32 s7, 0xfa00000
	v_add_co_u32_e32 v36, vcc, s7, v34
	s_mov_b32 s7, 0xfa10000
	s_nop 0
	v_addc_co_u32_e32 v37, vcc, 0, v35, vcc
	v_add_co_u32_e32 v38, vcc, s7, v34
	s_mov_b32 s7, 0xfa20000
	s_nop 0
	v_addc_co_u32_e32 v39, vcc, 0, v35, vcc
	global_load_dwordx4 v[62:65], v[36:37], off offset:256
	global_load_dwordx4 v[54:57], v[38:39], off offset:256
	v_add_co_u32_e32 v36, vcc, s7, v34
	s_mov_b32 s7, 0xfa30000
	s_nop 0
	v_addc_co_u32_e32 v37, vcc, 0, v35, vcc
	v_add_co_u32_e32 v34, vcc, s7, v34
	v_lshl_add_u64 v[38:39], v[94:95], 0, s[12:13]
	s_nop 0
	v_addc_co_u32_e32 v35, vcc, 0, v35, vcc
	global_load_dwordx4 v[66:69], v[36:37], off offset:256
	global_load_dwordx4 v[42:45], v[34:35], off offset:256
	v_add_co_u32_e32 v34, vcc, s87, v38
	v_lshl_add_u64 v[40:41], v[96:97], 0, s[12:13]
	s_nop 0
	v_addc_co_u32_e32 v35, vcc, 0, v39, vcc
	v_add_co_u32_e32 v36, vcc, s87, v40
	s_nop 1
	v_addc_co_u32_e32 v37, vcc, 0, v41, vcc
	global_load_dwordx4 v[78:81], v[34:35], off offset:256
	global_load_dwordx4 v[50:53], v[36:37], off offset:256
	v_add_co_u32_e32 v34, vcc, s94, v38
	s_nop 1
	v_addc_co_u32_e32 v35, vcc, 0, v39, vcc
	v_add_co_u32_e32 v36, vcc, s94, v40
	s_nop 1
	v_addc_co_u32_e32 v37, vcc, 0, v41, vcc
	global_load_dwordx4 v[70:73], v[34:35], off offset:256
	global_load_dwordx4 v[46:49], v[36:37], off offset:256
	v_add_co_u32_e32 v34, vcc, s95, v38
	s_nop 1
	v_addc_co_u32_e32 v35, vcc, 0, v39, vcc
	v_add_co_u32_e32 v36, vcc, s95, v40
	s_nop 1
	v_addc_co_u32_e32 v37, vcc, 0, v41, vcc
	v_add_co_u32_e32 v38, vcc, s92, v38
	global_load_dwordx4 v[58:61], v[34:35], off offset:256
	s_nop 0
	global_load_dwordx4 v[34:37], v[36:37], off offset:256
	v_addc_co_u32_e32 v39, vcc, 0, v39, vcc
	v_add_co_u32_e32 v74, vcc, s92, v40
	s_nop 1
	v_addc_co_u32_e32 v75, vcc, 0, v41, vcc
	global_load_dwordx4 v[38:41], v[38:39], off offset:256
	s_nop 0
	global_load_dwordx4 v[74:77], v[74:75], off offset:256
	ds_read_b128 v[104:107], v102
	ds_read_b128 v[108:111], v102 offset:4608
	s_waitcnt lgkmcnt(0)
	v_mfma_f32_32x32x16_bf16 v[2:17], v[104:107], v[108:111], v[2:17]
	ds_read_b128 v[108:111], v102 offset:9216
	s_waitcnt lgkmcnt(0)
	v_mfma_f32_32x32x16_bf16 v[18:33], v[104:107], v[108:111], v[18:33]
	ds_read_b128 v[104:107], v102 offset:32
	ds_read_b128 v[108:111], v102 offset:4640
	s_waitcnt lgkmcnt(0)
	v_mfma_f32_32x32x16_bf16 v[2:17], v[104:107], v[108:111], v[2:17]
	ds_read_b128 v[108:111], v102 offset:9248
	s_waitcnt lgkmcnt(0)
	v_mfma_f32_32x32x16_bf16 v[18:33], v[104:107], v[108:111], v[18:33]
	ds_read_b128 v[104:107], v102 offset:64
	ds_read_b128 v[108:111], v102 offset:4672
	s_waitcnt lgkmcnt(0)
	v_mfma_f32_32x32x16_bf16 v[2:17], v[104:107], v[108:111], v[2:17]
	ds_read_b128 v[108:111], v102 offset:9280
	s_waitcnt lgkmcnt(0)
	v_mfma_f32_32x32x16_bf16 v[18:33], v[104:107], v[108:111], v[18:33]
	ds_read_b128 v[104:107], v102 offset:96
	ds_read_b128 v[108:111], v102 offset:4704
	s_waitcnt lgkmcnt(0)
	v_mfma_f32_32x32x16_bf16 v[2:17], v[104:107], v[108:111], v[2:17]
	ds_read_b128 v[108:111], v102 offset:9312
	s_waitcnt lgkmcnt(0)
	v_mfma_f32_32x32x16_bf16 v[18:33], v[104:107], v[108:111], v[18:33]
	s_waitcnt vmcnt(12)
	ds_write_b128 v101, v[140:143]
	ds_write_b128 v101, v[132:135] offset:1152
	ds_write_b128 v101, v[144:147] offset:2304
	ds_write_b128 v101, v[120:123] offset:3456
	ds_write_b128 v101, v[156:159] offset:4608
	ds_write_b128 v101, v[128:131] offset:9216
	ds_write_b128 v101, v[148:151] offset:5760
	ds_write_b128 v101, v[124:127] offset:10368
	ds_write_b128 v101, v[136:139] offset:6912
	ds_write_b128 v101, v[112:115] offset:11520
	ds_write_b128 v101, v[116:119] offset:8064
	ds_write_b128 v101, v[152:155] offset:12672
	v_lshl_add_u64 v[112:113], v[92:93], 0, s[12:13]
	s_mov_b32 s7, 0xfa00000
	v_add_co_u32_e32 v114, vcc, s7, v112
	s_mov_b32 s7, 0xfa10000
	s_nop 0
	v_addc_co_u32_e32 v115, vcc, 0, v113, vcc
	v_add_co_u32_e32 v116, vcc, s7, v112
	s_mov_b32 s7, 0xfa20000
	s_nop 0
	v_addc_co_u32_e32 v117, vcc, 0, v113, vcc
	global_load_dwordx4 v[140:143], v[114:115], off offset:384
	global_load_dwordx4 v[132:135], v[116:117], off offset:384
	v_add_co_u32_e32 v114, vcc, s7, v112
	s_mov_b32 s7, 0xfa30000
	s_nop 0
	v_addc_co_u32_e32 v115, vcc, 0, v113, vcc
	v_add_co_u32_e32 v112, vcc, s7, v112
	v_lshl_add_u64 v[116:117], v[94:95], 0, s[12:13]
	s_nop 0
	v_addc_co_u32_e32 v113, vcc, 0, v113, vcc
	global_load_dwordx4 v[144:147], v[114:115], off offset:384
	global_load_dwordx4 v[120:123], v[112:113], off offset:384
	v_add_co_u32_e32 v112, vcc, s87, v116
	v_lshl_add_u64 v[118:119], v[96:97], 0, s[12:13]
	s_nop 0
	v_addc_co_u32_e32 v113, vcc, 0, v117, vcc
	v_add_co_u32_e32 v114, vcc, s87, v118
	s_nop 1
	v_addc_co_u32_e32 v115, vcc, 0, v119, vcc
	global_load_dwordx4 v[156:159], v[112:113], off offset:384
	global_load_dwordx4 v[128:131], v[114:115], off offset:384
	v_add_co_u32_e32 v112, vcc, s94, v116
	s_nop 1
	v_addc_co_u32_e32 v113, vcc, 0, v117, vcc
	v_add_co_u32_e32 v114, vcc, s94, v118
	s_nop 1
	v_addc_co_u32_e32 v115, vcc, 0, v119, vcc
	global_load_dwordx4 v[148:151], v[112:113], off offset:384
	global_load_dwordx4 v[124:127], v[114:115], off offset:384
	v_add_co_u32_e32 v112, vcc, s95, v116
	s_nop 1
	v_addc_co_u32_e32 v113, vcc, 0, v117, vcc
	v_add_co_u32_e32 v114, vcc, s95, v118
	s_nop 1
	v_addc_co_u32_e32 v115, vcc, 0, v119, vcc
	v_add_co_u32_e32 v116, vcc, s92, v116
	global_load_dwordx4 v[136:139], v[112:113], off offset:384
	s_nop 0
	global_load_dwordx4 v[112:115], v[114:115], off offset:384
	v_addc_co_u32_e32 v117, vcc, 0, v117, vcc
	v_add_co_u32_e32 v152, vcc, s92, v118
	s_nop 1
	v_addc_co_u32_e32 v153, vcc, 0, v119, vcc
	global_load_dwordx4 v[116:119], v[116:117], off offset:384
	s_nop 0
	global_load_dwordx4 v[152:155], v[152:153], off offset:384
	ds_read_b128 v[104:107], v102
	ds_read_b128 v[108:111], v102 offset:4608
	s_add_u32 s12, s12, 0x100
	s_addc_u32 s13, s13, 0
	s_cmpk_eq_i32 s12, 0x300
	s_waitcnt lgkmcnt(0)
; #define LAS __attribute__((address_space(3)))
; #define MFMA32(a, b, c) __builtin_amdgcn_mfma_f32_32x32x16_bf16((a), (b), (c), 0, 0, 0)
;     ...
; #pragma unroll
;                 for (int i = 0; i < 4; ++i) { *(LAS u32x4*)(SB0 + (8 * i + (lane >> 3)) * PITCH + 16 * (lane & 7)) = bb0[i]; *(LAS u32x4*)(SB1 + (8 * i + (lane >> 3)) * PITCH + 16 * (lane & 7)) = bb1[i]; }
;                 __builtin_amdgcn_sched_barrier(0);
;                 if (kb + 1 < nb) SG_LOAD(kb + 1);
;                 __builtin_amdgcn_sched_barrier(0);
; #pragma unroll
;                 for (int j = 0; j < 4; ++j) {
;                     const bf16x8 af = *(const LAS bf16x8*)(SA + r32 * PITCH + 32 * j + 16 * hi);
;                     const bf16x8 f0 = *(const LAS bf16x8*)(SB0 + r32 * PITCH + 32 * j + 16 * hi), f1 = *(const LAS bf16x8*)(SB1 + r32 * PITCH + 32 * j + 16 * hi);
;                     acc0 = MFMA32(af, f0, acc0); acc1 = MFMA32(af, f1, acc1);
;                 }
	v_mfma_f32_32x32x16_bf16 v[2:17], v[104:107], v[108:111], v[2:17]
	ds_read_b128 v[108:111], v102 offset:9216
	s_waitcnt lgkmcnt(0)
	v_mfma_f32_32x32x16_bf16 v[18:33], v[104:107], v[108:111], v[18:33]
	ds_read_b128 v[104:107], v102 offset:32
	ds_read_b128 v[108:111], v102 offset:4640
	s_waitcnt lgkmcnt(0)
	v_mfma_f32_32x32x16_bf16 v[2:17], v[104:107], v[108:111], v[2:17]
	ds_read_b128 v[108:111], v102 offset:9248
	s_waitcnt lgkmcnt(0)
	v_mfma_f32_32x32x16_bf16 v[18:33], v[104:107], v[108:111], v[18:33]
	ds_read_b128 v[104:107], v102 offset:64
	ds_read_b128 v[108:111], v102 offset:4672
	s_waitcnt lgkmcnt(0)
	v_mfma_f32_32x32x16_bf16 v[2:17], v[104:107], v[108:111], v[2:17]
	ds_read_b128 v[108:111], v102 offset:9280
	s_waitcnt lgkmcnt(0)
	v_mfma_f32_32x32x16_bf16 v[18:33], v[104:107], v[108:111], v[18:33]
	ds_read_b128 v[104:107], v102 offset:96
	ds_read_b128 v[108:111], v102 offset:4704
	s_waitcnt lgkmcnt(0)
	v_mfma_f32_32x32x16_bf16 v[2:17], v[104:107], v[108:111], v[2:17]
	ds_read_b128 v[108:111], v102 offset:9312
	s_waitcnt lgkmcnt(0)
	v_mfma_f32_32x32x16_bf16 v[18:33], v[104:107], v[108:111], v[18:33]
	s_cbranch_scc0 .LBB0_1347
	s_waitcnt vmcnt(12)
	ds_write_b128 v101, v[62:65]
	ds_write_b128 v101, v[54:57] offset:1152
	ds_write_b128 v101, v[66:69] offset:2304
	ds_write_b128 v101, v[42:45] offset:3456
	ds_write_b128 v101, v[78:81] offset:4608
	ds_write_b128 v101, v[50:53] offset:9216
	ds_write_b128 v101, v[70:73] offset:5760
	ds_write_b128 v101, v[46:49] offset:10368
	ds_write_b128 v101, v[58:61] offset:6912
	ds_write_b128 v101, v[34:37] offset:11520
	ds_write_b128 v101, v[38:41] offset:8064
	ds_write_b128 v101, v[74:77] offset:12672
	s_ashr_i32 s7, s6, 31
	ds_read_b128 v[104:107], v102
	ds_read_b128 v[108:111], v102 offset:4608
	s_waitcnt lgkmcnt(0)
	v_mfma_f32_32x32x16_bf16 v[2:17], v[104:107], v[108:111], v[2:17]
	ds_read_b128 v[108:111], v102 offset:9216
	s_waitcnt lgkmcnt(0)
	v_mfma_f32_32x32x16_bf16 v[18:33], v[104:107], v[108:111], v[18:33]
	ds_read_b128 v[104:107], v102 offset:32
	ds_read_b128 v[108:111], v102 offset:4640
	s_waitcnt lgkmcnt(0)
	v_mfma_f32_32x32x16_bf16 v[2:17], v[104:107], v[108:111], v[2:17]
	ds_read_b128 v[108:111], v102 offset:9248
	s_waitcnt lgkmcnt(0)
	v_mfma_f32_32x32x16_bf16 v[18:33], v[104:107], v[108:111], v[18:33]
	ds_read_b128 v[104:107], v102 offset:64
	ds_read_b128 v[108:111], v102 offset:4672
	s_waitcnt lgkmcnt(0)
	v_mfma_f32_32x32x16_bf16 v[2:17], v[104:107], v[108:111], v[2:17]
	ds_read_b128 v[108:111], v102 offset:9280
	s_waitcnt lgkmcnt(0)
	v_mfma_f32_32x32x16_bf16 v[18:33], v[104:107], v[108:111], v[18:33]
	ds_read_b128 v[104:107], v102 offset:96
	ds_read_b128 v[108:111], v102 offset:4704
	s_waitcnt lgkmcnt(0)
	v_mfma_f32_32x32x16_bf16 v[2:17], v[104:107], v[108:111], v[2:17]
	ds_read_b128 v[108:111], v102 offset:9312
	s_waitcnt lgkmcnt(0)
	v_mfma_f32_32x32x16_bf16 v[18:33], v[104:107], v[108:111], v[18:33]
	s_waitcnt vmcnt(0)
	ds_write_b128 v101, v[140:143]
	ds_write_b128 v101, v[132:135] offset:1152
	ds_write_b128 v101, v[144:147] offset:2304
	ds_write_b128 v101, v[120:123] offset:3456
	ds_write_b128 v101, v[156:159] offset:4608
	ds_write_b128 v101, v[128:131] offset:9216
	ds_write_b128 v101, v[148:151] offset:5760
	ds_write_b128 v101, v[124:127] offset:10368
	ds_write_b128 v101, v[136:139] offset:6912
	ds_write_b128 v101, v[112:115] offset:11520
	ds_write_b128 v101, v[116:119] offset:8064
	ds_write_b128 v101, v[152:155] offset:12672
	ds_read_b128 v[104:107], v102
	ds_read_b128 v[108:111], v102 offset:4608
	s_waitcnt lgkmcnt(0)
	v_mfma_f32_32x32x16_bf16 v[2:17], v[104:107], v[108:111], v[2:17]
	ds_read_b128 v[108:111], v102 offset:9216
	s_waitcnt lgkmcnt(0)
	v_mfma_f32_32x32x16_bf16 v[18:33], v[104:107], v[108:111], v[18:33]
	ds_read_b128 v[104:107], v102 offset:32
	ds_read_b128 v[108:111], v102 offset:4640
	s_waitcnt lgkmcnt(0)
	v_mfma_f32_32x32x16_bf16 v[2:17], v[104:107], v[108:111], v[2:17]
	ds_read_b128 v[108:111], v102 offset:9248
	s_waitcnt lgkmcnt(0)
	v_mfma_f32_32x32x16_bf16 v[18:33], v[104:107], v[108:111], v[18:33]
	ds_read_b128 v[104:107], v102 offset:64
	ds_read_b128 v[108:111], v102 offset:4672
	s_waitcnt lgkmcnt(0)
	v_mfma_f32_32x32x16_bf16 v[2:17], v[104:107], v[108:111], v[2:17]
	ds_read_b128 v[108:111], v102 offset:9280
	s_waitcnt lgkmcnt(0)
	v_mfma_f32_32x32x16_bf16 v[18:33], v[104:107], v[108:111], v[18:33]
	ds_read_b128 v[104:107], v102 offset:96
	ds_read_b128 v[108:111], v102 offset:4704
	s_waitcnt lgkmcnt(0)
	v_mfma_f32_32x32x16_bf16 v[2:17], v[104:107], v[108:111], v[2:17]
	ds_read_b128 v[108:111], v102 offset:9312
	s_waitcnt lgkmcnt(0)
	v_mfma_f32_32x32x16_bf16 v[18:33], v[104:107], v[108:111], v[18:33]
	s_branch .LBB0_1350
